# tail fill, variant: layer-1 w_in also converted in the ph1 tail (7 items per wave), ph2 converts nothing
# speedup vs baseline: 1.0201x; 1.0086x over previous
; __global__ void __launch_bounds__(NWAVES * 64, 2) fwd_kernel(Args args) {
;     ...
;         if ((PHM & 1) && rep == 0 && (ph == 0 || ph == 2)) {
;             constexpr int CV_IN = (D / 64) * (INW / 32), CV_ALL = 2 * (CV_IN + 2 * ((512 / 64) * (D / 32)) + (D / 64) * (D / 32) + (D / 64) * (NUP / 32) + (DFF / 64) * (D / 32));
;             __syncthreads();
;             p0_convert(a, lds, gw, NGW, wave, lane, ph == 0 ? 0 : CV_IN, ph == 0 ? CV_IN : CV_ALL, ph == 0);
.LBB0_378:
	s_andn2_b64 vcc, exec, s[18:19]
	s_cbranch_vccnz cvx_check
	v_readlane_b32 s2, v254, 59
	v_readlane_b32 s3, v254, 60
	s_and_b64 s[2:3], s[2:3], exec
	s_movk_i32 s2, 0x780
	v_readlane_b32 s18, v254, 61
	s_cselect_b32 s3, 0, 0x780
	s_cselect_b32 s2, 0x780, s2
	s_ashr_i32 s18, s18, 6
	s_lshl_b32 s19, s21, 3
	s_add_i32 s26, s18, s19
	s_add_i32 s3, s26, s3

; __global__ void __launch_bounds__(NWAVES * 64, 2) fwd_kernel(Args args) {
;     ...
;             p0_convert(a, lds, gw, NGW, wave, lane, ph == 0 ? 0 : CV_IN, ph == 0 ? CV_IN : CV_ALL, ph == 0);
cvx_l0:
	s_movk_i32 s3, 0x780
	s_movk_i32 s2, 0x2380
